# ffn_up K-loop: the next K-tile's eight LDS-DMA pieces are issued four behind the first and four behind the second fragment-read group (were two behind each of four groups), so they land before the nex
# speedup vs baseline: 1.0141x; 1.0092x over previous
; #define MFMA16(a, b, c) __builtin_amdgcn_mfma_f32_16x16x32_bf16((a), (b), (c), 0, 0, 0)
; #define RAW_BARRIER() do { asm volatile("s_waitcnt lgkmcnt(0)" ::: "memory"); __builtin_amdgcn_s_barrier(); } while (0)
; template <int AMODE, bool SWAPO = true>
; DI void mainloop_dma16(f32x4 (&acc)[4][2][2][2], const TD& c, const TD& n, bool hasn, bool primed, int& s, int tid) {
;     ...
;     for (int kt = 0; kt < nk; ++kt) {
;         asm volatile("s_waitcnt vmcnt(0)" ::: "memory");
;         RAW_BARRIER();
;         const int ns = s ^ 1, nkt = kt + 1;
;         const bool doload = nkt < nk;
;         const char* sb = smem + s * C::STAGE;
; #pragma unroll
;         for (int k2 = 0; k2 < 2; ++k2) {
;             const int co = ((4 * k2 + q) ^ key) << 4;
;             bf16x8 fw[2][2];
; #pragma unroll
;             for (int ni = 0; ni < 2; ++ni)
; #pragma unroll
;                 for (int rh = 0; rh < 2; ++rh) fw[ni][rh] = *(const bf16x8*)(sb + b_off + (ni * 32 + rh * 16) * 128 + co);
; #pragma unroll
;             for (int mh = 0; mh < 2; ++mh) {
;                 bf16x8 fx[2][2];
; #pragma unroll
;                 for (int m2 = 0; m2 < 2; ++m2)
; #pragma unroll
;                     for (int ch = 0; ch < 2; ++ch) fx[m2][ch] = *(const bf16x8*)(sb + a_off + ((2 * mh + m2) * 32 + ch * 16) * 128 + co);
;                 asm volatile("" ::: "memory");
;                 if (doload) { const int p0 = (2 * k2 + mh) * 2; piece(c, ao, bo, nkt, ns, p0); piece(c, ao, bo, nkt, ns, p0 + 1); }
;                 asm volatile("" ::: "memory");
; #pragma unroll
;                 for (int m2 = 0; m2 < 2; ++m2)
; #pragma unroll
;                     for (int ni = 0; ni < 2; ++ni)
; #pragma unroll
;                         for (int rh = 0; rh < 2; ++rh)
; #pragma unroll
;                             for (int ch = 0; ch < 2; ++ch)
;                                 acc[2 * mh + m2][ni][rh][ch] = SWAPO ? MFMA16(fw[ni][rh], fx[m2][ch], acc[2 * mh + m2][ni][rh][ch]) : MFMA16(fx[m2][ch], fw[ni][rh], acc[2 * mh + m2][ni][rh][ch]);
;             }
.LBB0_1196:
	s_cmp_lt_u32 s27, 15
	s_cselect_b64 s[18:19], -1, 0
	s_lshl_b32 s0, s28, 16
	s_add_i32 s1, s0, 16
	v_add3_u32 v192, s1, v181, v179
	v_add3_u32 v191, s1, v180, v179
	s_waitcnt vmcnt(0)
	v_add_u32_e32 v128, v192, v189
	v_add_u32_e32 v193, v191, v189
	s_waitcnt lgkmcnt(0)
	s_barrier
	ds_read_b128 v[140:143], v128 offset:32768
	ds_read_b128 v[136:139], v128 offset:34816
	ds_read_b128 v[132:135], v128 offset:36864
	ds_read_b128 v[128:131], v128 offset:38912
	ds_read_b128 v[152:155], v193
	ds_read_b128 v[156:159], v193 offset:2048
	ds_read_b128 v[144:147], v193 offset:4096
	ds_read_b128 v[148:151], v193 offset:6144
	s_xor_b32 s0, s0, 0x10000
	s_cmp_gt_u32 s27, 14
	v_add_u32_e32 v176, s0, v188
	s_cbranch_scc1 .LBB0_1198
	v_lshl_add_u64 v[194:195], v[160:161], 0, s[4:5]
	v_readfirstlane_b32 s0, v176
	s_mov_b32 m0, s0
	s_nop 0
	global_load_lds_dwordx4 v[194:195], off
	v_add_u32_e32 v196, 0x400, v176
	v_lshl_add_u64 v[194:195], v[162:163], 0, s[4:5]
	v_readfirstlane_b32 s0, v196
	s_mov_b32 m0, s0
	s_nop 0
	global_load_lds_dwordx4 v[194:195], off
	v_add_u32_e32 v196, 0x800, v176
	v_lshl_add_u64 v[194:195], v[164:165], 0, s[4:5]
	v_readfirstlane_b32 s0, v196
	s_mov_b32 m0, s0
	s_nop 0
	global_load_lds_dwordx4 v[194:195], off
	v_add_u32_e32 v196, 0xc00, v176
	v_lshl_add_u64 v[194:195], v[166:167], 0, s[4:5]
	v_readfirstlane_b32 s0, v196
	s_mov_b32 m0, s0
	s_nop 0
	global_load_lds_dwordx4 v[194:195], off
.LBB0_1198:
	s_waitcnt lgkmcnt(0)
	v_mfma_f32_16x16x32_bf16 v[120:123], v[152:155], v[140:143], v[120:123]
	s_andn2_b64 vcc, exec, s[18:19]
	v_mfma_f32_16x16x32_bf16 v[112:115], v[156:159], v[140:143], v[112:115]
	v_mfma_f32_16x16x32_bf16 v[56:59], v[152:155], v[136:139], v[56:59]
	v_mfma_f32_16x16x32_bf16 v[48:51], v[156:159], v[136:139], v[48:51]
	v_mfma_f32_16x16x32_bf16 v[124:127], v[152:155], v[132:135], v[124:127]
	v_mfma_f32_16x16x32_bf16 v[116:119], v[156:159], v[132:135], v[116:119]
	v_mfma_f32_16x16x32_bf16 v[60:63], v[152:155], v[128:131], v[60:63]
	v_mfma_f32_16x16x32_bf16 v[52:55], v[156:159], v[128:131], v[52:55]
	v_mfma_f32_16x16x32_bf16 v[104:107], v[144:147], v[140:143], v[104:107]
	v_mfma_f32_16x16x32_bf16 v[96:99], v[148:151], v[140:143], v[96:99]
	v_mfma_f32_16x16x32_bf16 v[40:43], v[144:147], v[136:139], v[40:43]
	v_mfma_f32_16x16x32_bf16 v[32:35], v[148:151], v[136:139], v[32:35]
	v_mfma_f32_16x16x32_bf16 v[108:111], v[144:147], v[132:135], v[108:111]
	v_mfma_f32_16x16x32_bf16 v[100:103], v[148:151], v[132:135], v[100:103]
	v_mfma_f32_16x16x32_bf16 v[44:47], v[144:147], v[128:131], v[44:47]
	v_mfma_f32_16x16x32_bf16 v[36:39], v[148:151], v[128:131], v[36:39]
	ds_read_b128 v[152:155], v193 offset:8192
	ds_read_b128 v[156:159], v193 offset:10240
	ds_read_b128 v[144:147], v193 offset:12288
	ds_read_b128 v[148:151], v193 offset:14336
	v_cndmask_b32_e64 v193, 0, 1, s[18:19]
	v_cmp_ne_u32_e64 s[0:1], 1, v193
	s_cbranch_vccnz .LBB0_1200
	v_add_u32_e32 v196, 0x8000, v176
	v_lshl_add_u64 v[194:195], v[168:169], 0, s[4:5]
	v_readfirstlane_b32 s18, v196
	s_mov_b32 m0, s18
	s_nop 0
	global_load_lds_dwordx4 v[194:195], off
	v_add_u32_e32 v196, 0x8400, v176
	v_lshl_add_u64 v[194:195], v[170:171], 0, s[4:5]
	v_readfirstlane_b32 s18, v196
	s_mov_b32 m0, s18
	s_nop 0
	global_load_lds_dwordx4 v[194:195], off
	v_add_u32_e32 v196, 0x8800, v176
	v_lshl_add_u64 v[194:195], v[172:173], 0, s[4:5]
	v_readfirstlane_b32 s18, v196
	s_mov_b32 m0, s18
	s_nop 0
	global_load_lds_dwordx4 v[194:195], off
	v_add_u32_e32 v196, 0x8c00, v176
	v_lshl_add_u64 v[194:195], v[174:175], 0, s[4:5]
	v_readfirstlane_b32 s18, v196
	s_mov_b32 m0, s18
	s_nop 0
	global_load_lds_dwordx4 v[194:195], off

; #define MFMA16(a, b, c) __builtin_amdgcn_mfma_f32_16x16x32_bf16((a), (b), (c), 0, 0, 0)
; template <int AMODE, bool SWAPO = true>
; DI void mainloop_dma16(f32x4 (&acc)[4][2][2][2], const TD& c, const TD& n, bool hasn, bool primed, int& s, int tid) {
;     ...
; #pragma unroll
;         for (int k2 = 0; k2 < 2; ++k2) {
;             const int co = ((4 * k2 + q) ^ key) << 4;
;             bf16x8 fw[2][2];
; #pragma unroll
;             for (int ni = 0; ni < 2; ++ni)
; #pragma unroll
;                 for (int rh = 0; rh < 2; ++rh) fw[ni][rh] = *(const bf16x8*)(sb + b_off + (ni * 32 + rh * 16) * 128 + co);
; #pragma unroll
;             for (int mh = 0; mh < 2; ++mh) {
;                 bf16x8 fx[2][2];
; #pragma unroll
;                 for (int m2 = 0; m2 < 2; ++m2)
; #pragma unroll
;                     for (int ch = 0; ch < 2; ++ch) fx[m2][ch] = *(const bf16x8*)(sb + a_off + ((2 * mh + m2) * 32 + ch * 16) * 128 + co);
;                 asm volatile("" ::: "memory");
;                 if (doload) { const int p0 = (2 * k2 + mh) * 2; piece(c, ao, bo, nkt, ns, p0); piece(c, ao, bo, nkt, ns, p0 + 1); }
;                 asm volatile("" ::: "memory");
; #pragma unroll
;                 for (int m2 = 0; m2 < 2; ++m2)
; #pragma unroll
;                     for (int ni = 0; ni < 2; ++ni)
; #pragma unroll
;                         for (int rh = 0; rh < 2; ++rh)
; #pragma unroll
;                             for (int ch = 0; ch < 2; ++ch)
;                                 acc[2 * mh + m2][ni][rh][ch] = SWAPO ? MFMA16(fw[ni][rh], fx[m2][ch], acc[2 * mh + m2][ni][rh][ch]) : MFMA16(fx[m2][ch], fw[ni][rh], acc[2 * mh + m2][ni][rh][ch]);
;             }
.LBB0_1202:
	s_waitcnt lgkmcnt(0)
	v_mfma_f32_16x16x32_bf16 v[120:123], v[152:155], v[140:143], v[120:123]
	s_and_b64 vcc, exec, s[0:1]
	v_mfma_f32_16x16x32_bf16 v[112:115], v[156:159], v[140:143], v[112:115]
	v_mfma_f32_16x16x32_bf16 v[56:59], v[152:155], v[144:147], v[56:59]
	v_mfma_f32_16x16x32_bf16 v[48:51], v[156:159], v[144:147], v[48:51]
	v_mfma_f32_16x16x32_bf16 v[124:127], v[152:155], v[136:139], v[124:127]
	v_mfma_f32_16x16x32_bf16 v[116:119], v[156:159], v[136:139], v[116:119]
	v_mfma_f32_16x16x32_bf16 v[60:63], v[152:155], v[128:131], v[60:63]
	v_mfma_f32_16x16x32_bf16 v[52:55], v[156:159], v[128:131], v[52:55]
	v_mfma_f32_16x16x32_bf16 v[104:107], v[132:135], v[140:143], v[104:107]
	v_mfma_f32_16x16x32_bf16 v[96:99], v[148:151], v[140:143], v[96:99]
	v_mfma_f32_16x16x32_bf16 v[40:43], v[132:135], v[144:147], v[40:43]
	v_mfma_f32_16x16x32_bf16 v[32:35], v[148:151], v[144:147], v[32:35]
	v_mfma_f32_16x16x32_bf16 v[108:111], v[132:135], v[136:139], v[108:111]
	v_mfma_f32_16x16x32_bf16 v[100:103], v[148:151], v[136:139], v[100:103]
	v_mfma_f32_16x16x32_bf16 v[44:47], v[132:135], v[128:131], v[44:47]
	v_mfma_f32_16x16x32_bf16 v[36:39], v[148:151], v[128:131], v[36:39]
	ds_read_b128 v[152:155], v191 offset:8192
	ds_read_b128 v[156:159], v191 offset:10240
	ds_read_b128 v[148:151], v191 offset:12288
	ds_read_b128 v[132:135], v191 offset:14336
	s_cbranch_vccnz .LBB0_1195
	s_branch .LBB0_1195
